# gated-DeltaNet: output stores issued one iteration later, right after the loop's vmcnt(0), so that wait never covers a fresh store
# baseline (speedup 1.0000x reference)
; __device__ __forceinline__ void gdn_item(const Params& p, int item, float* sm) {
;     ...
;   for (int ch = 0; ch < NCH; ch++) {
;     const int bi = ch & 1;
;     const int t0 = PADR + ch * TC;
;     if (ch + 1 < NCH) GDN_LOAD(t0 + TC)
;     {
;       const float* bq = sm + bi * BUF;
;       const float* bk = bq + TC * 128;
;       const float* bv = bq + 2 * TC * 128;
;       const float* bg = bv + TC * 16;
;       float* bo = sm + bi * BUF + 2 * TC * 128 + TC * 16 + 2 * TC;
;       float oreg[TC];
; #pragma unroll
;       for (int t = 0; t < TC; t++) {
;         const float4 k0 = *(const float4*)(bk + t * 128 + sub * 4);
;         const float4 k1 = *(const float4*)(bk + t * 128 + 64 + sub * 4);
;         const float4 q0 = *(const float4*)(bq + t * 128 + sub * 4);
;         const float4 q1 = *(const float4*)(bq + t * 128 + 64 + sub * 4);
;         const float v = bv[t * 16 + cw];
;         const float g = bg[t], be = bg[TC + t];
;         const float qk = bo[TC * 16 + t];
;         float pa = k0.x * S[0] + k0.y * S[1];
;         float pb2 = k0.z * S[2] + k0.w * S[3];
;         float qa = q0.x * S[0] + q0.y * S[1];
;         float qb2 = q0.z * S[2] + q0.w * S[3];
;         pa += k1.x * S[4] + k1.y * S[5];
;         pb2 += k1.z * S[6] + k1.w * S[7];
;         qa += q1.x * S[4] + q1.y * S[5];
;         qb2 += q1.z * S[6] + q1.w * S[7];
;         const float ks = dpp_sum16(pa + pb2);
;         const float qs = dpp_sum16(qa + qb2);
;         const float coef = be * (v - g * ks);
;         const float oo = g * qs + coef * qk;
;         S[0] = g * S[0] + coef * k0.x; S[1] = g * S[1] + coef * k0.y; S[2] = g * S[2] + coef * k0.z; S[3] = g * S[3] + coef * k0.w;
;         S[4] = g * S[4] + coef * k1.x; S[5] = g * S[5] + coef * k1.y; S[6] = g * S[6] + coef * k1.z; S[7] = g * S[7] + coef * k1.w;
;         oreg[t] = oo * 0.08838834764831845f;
;     ...
;     {
;       const float ov = sm[bi * BUF + 2 * TC * 128 + TC * 16 + 2 * TC + ltt * 16 + lseg];
;       O[(rowb + t0 + ltt) * D + 512 + h * 128 + c0 + lseg] = f2bf(ov);
;     }
.Lgd_chunk:
	v_add_u32_e32 v141, s1, v151
	v_add_u32_e32 v142, s1, v152
	v_add_u32_e32 v143, s1, v153
	v_add_u32_e32 v144, s1, v154
	v_mov_b32_e32 v145, s1
	s_xor_b32 s2, s1, 0x4500
	s_and_b32 s12, s0, 1
	s_mul_i32 s12, s12, 0x3000
	v_add_u32_e32 v146, s12, v155
	v_add_u32_e32 v147, s12, v156
	ds_read_b128 v[20:23], v141 offset:8192
	ds_read_b128 v[28:31], v141 offset:0
	ds_read_b128 v[24:27], v141 offset:8256
	ds_read_b128 v[32:35], v141 offset:64
	v_add_u32_e32 v148, s2, v157
	v_add_u32_e32 v149, s2, v158
	v_add_u32_e32 v150, s2, v159
	s_waitcnt lgkmcnt(0)
	v_mfma_f32_16x16x4_f32 v[60:63], v20, v12, 0
	ds_read_b32 v36, v142 offset:8192
	v_mfma_f32_16x16x4_f32 v[64:67], v28, v12, 0
	ds_read_b32 v37, v142 offset:8704
	v_mfma_f32_16x16x4_f32 v[60:63], v21, v13, v[60:63]
	ds_read_b32 v38, v142 offset:9216
	v_mfma_f32_16x16x4_f32 v[64:67], v29, v13, v[64:67]
	ds_read_b32 v39, v142 offset:9728
	s_waitcnt vmcnt(0)
	s_cmp_eq_u32 s0, 0
	s_cbranch_scc1 .Lgd_nost
	s_add_i32 s12, s0, 3
	s_and_b32 s12, s12, 3
	s_cmp_eq_u32 s12, s100
	s_cbranch_scc0 .Lgd_nosw
	global_store_short v57, v104, s[8:9]
	global_store_short v57, v105, s[8:9] offset:2048
	global_store_short v58, v106, s[8:9]
	global_store_short v58, v107, s[8:9] offset:2048

; __device__ __forceinline__ void gdn_item(const Params& p, int item, float* sm) {
;     ...
;       for (int t = 0; t < TC; t++) {
;         const float4 k0 = *(const float4*)(bk + t * 128 + sub * 4);
;         const float4 k1 = *(const float4*)(bk + t * 128 + 64 + sub * 4);
;         const float4 q0 = *(const float4*)(bq + t * 128 + sub * 4);
;         const float4 q1 = *(const float4*)(bq + t * 128 + 64 + sub * 4);
;         const float v = bv[t * 16 + cw];
;         const float g = bg[t], be = bg[TC + t];
;         const float qk = bo[TC * 16 + t];
;         float pa = k0.x * S[0] + k0.y * S[1];
;         float pb2 = k0.z * S[2] + k0.w * S[3];
;         float qa = q0.x * S[0] + q0.y * S[1];
;         float qb2 = q0.z * S[2] + q0.w * S[3];
;         pa += k1.x * S[4] + k1.y * S[5];
;         pb2 += k1.z * S[6] + k1.w * S[7];
;         qa += q1.x * S[4] + q1.y * S[5];
;         qb2 += q1.z * S[6] + q1.w * S[7];
;         const float ks = dpp_sum16(pa + pb2);
;         const float qs = dpp_sum16(qa + qb2);
;         const float coef = be * (v - g * ks);
;         const float oo = g * qs + coef * qk;
;         S[0] = g * S[0] + coef * k0.x; S[1] = g * S[1] + coef * k0.y; S[2] = g * S[2] + coef * k0.z; S[3] = g * S[3] + coef * k0.w;
;         S[4] = g * S[4] + coef * k1.x; S[5] = g * S[5] + coef * k1.y; S[6] = g * S[6] + coef * k1.z; S[7] = g * S[7] + coef * k1.w;
;         oreg[t] = oo * 0.08838834764831845f;
;       }
;       if (sub == 0) {
; #pragma unroll
;         for (int t = 0; t < TC; t++) bo[t * 16 + cw] = oreg[t];
;       }
;     }
;     if (ch + 1 < NCH) GDN_STORE(bi ^ 1)
;     __syncthreads();
;     {
;       const float ov = sm[bi * BUF + 2 * TC * 128 + TC * 16 + 2 * TC + ltt * 16 + lseg];
;       O[(rowb + t0 + ltt) * D + 512 + h * 128 + c0 + lseg] = f2bf(ov);
;     }
.Lgd_nost:
	v_lshlrev_b32_e32 v120, 16, v108
	v_and_b32_e32 v121, 0xffff0000, v108
	v_mfma_f32_16x16x4_f32 v[60:63], v22, v14, v[60:63]
	ds_read_b32 v40, v142 offset:8256
	v_lshlrev_b32_e32 v122, 16, v109
	v_and_b32_e32 v123, 0xffff0000, v109
	v_lshlrev_b32_e32 v124, 16, v110
	v_mfma_f32_16x16x4_f32 v[64:67], v30, v14, v[64:67]
	ds_read_b32 v41, v142 offset:8768
	v_and_b32_e32 v125, 0xffff0000, v110
	v_lshlrev_b32_e32 v126, 16, v111
	v_and_b32_e32 v127, 0xffff0000, v111
	v_lshlrev_b32_e32 v128, 16, v112
	v_mfma_f32_16x16x4_f32 v[60:63], v23, v15, v[60:63]
	ds_read_b32 v42, v142 offset:9280
	v_and_b32_e32 v129, 0xffff0000, v112
	v_lshlrev_b32_e32 v130, 16, v113
	v_and_b32_e32 v131, 0xffff0000, v113
	v_mfma_f32_16x16x4_f32 v[64:67], v31, v15, v[64:67]
	ds_read_b32 v43, v142 offset:9792
	v_lshlrev_b32_e32 v132, 16, v114
	v_and_b32_e32 v133, 0xffff0000, v114
	v_lshlrev_b32_e32 v134, 16, v115
	v_and_b32_e32 v135, 0xffff0000, v115
	v_mfma_f32_16x16x4_f32 v[60:63], v24, v16, v[60:63]
	ds_read_b128 v[44:47], v143 offset:16384
	v_mov_b32_e32 v136, v117
	v_lshlrev_b32_e32 v137, 16, v116
	s_nop 0
	v_mfma_f32_16x16x4_f32 v[64:67], v32, v16, v[64:67]
	ds_read_b128 v[48:51], v144 offset:17408
	v_add_f32_dpp v136, v136, v136 row_shr:1 row_mask:0xf bank_mask:0xf bound_ctrl:1
	s_nop 1
	v_add_f32_dpp v136, v136, v136 row_shr:2 row_mask:0xf bank_mask:0xf bound_ctrl:1
	s_nop 1
	v_mfma_f32_16x16x4_f32 v[60:63], v25, v17, v[60:63]
	ds_read_b128 v[52:55], v144 offset:17472
	v_add_f32_dpp v136, v136, v136 row_shr:4 row_mask:0xf bank_mask:0xf bound_ctrl:1
	s_nop 1
	v_add_f32_dpp v136, v136, v136 row_shr:8 row_mask:0xf bank_mask:0xf bound_ctrl:1
	v_mfma_f32_16x16x4_f32 v[64:67], v33, v17, v[64:67]
	ds_read_b32 v56, v145 offset:17596
	s_nop 0
	v_max_f32_e32 v136, 0xc2a00000, v136
	v_mul_f32_e32 v136, 0x3fb8aa3b, v136
	v_exp_f32_e32 v138, v136
	v_mfma_f32_16x16x4_f32 v[60:63], v26, v18, v[60:63]
	v_exp_f32_e64 v139, -v136
	s_nop 0
	v_mul_f32_e32 v136, 0x3db504f3, v138
	v_mfma_f32_16x16x4_f32 v[64:67], v34, v18, v[64:67]
	ds_write_b128 v148, v[120:123]
	ds_write_b128 v148, v[124:127] offset:16
	ds_write_b128 v148, v[128:131] offset:8192
	ds_write_b128 v148, v[132:135] offset:8208
	v_mfma_f32_16x16x4_f32 v[60:63], v27, v19, v[60:63]
	ds_write_b32 v149, v137
	ds_write_b32 v150, v139 offset:17408
	ds_write_b32 v150, v138 offset:17536
	v_mfma_f32_16x16x4_f32 v[64:67], v35, v19, v[64:67]
	ds_write_b32 v150, v136 offset:17472
	global_load_dwordx4 v[108:111], v118, s[4:5]
	global_load_dwordx4 v[112:115], v118, s[4:5] offset:1024
	global_load_ushort v116, v119, s[4:5]
	global_load_dword v117, v140, s[6:7]
	s_cmp_lt_u32 s0, 0x1fe
	s_cselect_b32 s12, 0xc000, 0
	s_cselect_b32 s101, 0x200, 0
	s_add_u32 s4, s4, s12
	s_addc_u32 s5, s5, 0
	s_add_u32 s6, s6, s101
	s_addc_u32 s7, s7, 0
	s_nop 3
	ds_write_b128 v146, v[60:63]
	ds_write_b128 v146, v[64:67] offset:1024
	s_waitcnt lgkmcnt(0)
	s_barrier
	ds_read_b128 v[72:75], v147 offset:0
	ds_read_b128 v[76:79], v147 offset:3072
	ds_read_b128 v[80:83], v147 offset:6144
	ds_read_b128 v[84:87], v147 offset:9216
	s_waitcnt lgkmcnt(0)
	v_add_f32_e32 v72, v72, v76
	v_add_f32_e32 v80, v80, v84
	v_add_f32_e32 v73, v73, v77
	v_add_f32_e32 v81, v81, v85
	v_add_f32_e32 v74, v74, v78
	v_add_f32_e32 v82, v82, v86
	v_add_f32_e32 v75, v75, v79
	v_add_f32_e32 v83, v83, v87
	v_add_f32_e32 v72, v72, v80
	v_add_f32_e32 v73, v73, v81
	v_add_f32_e32 v74, v74, v82
	v_add_f32_e32 v75, v75, v83
	v_fma_f32 v96, v44, v48, -v72
	v_fma_f32 v97, v45, v49, -v73
	v_fma_f32 v98, v46, v50, -v74
	v_fma_f32 v99, v47, v51, -v75
	s_nop 1
	v_mfma_f32_16x16x4_f32 v[100:103], v88, v96, 0
	v_mfma_f32_16x16x4_f32 v[100:103], v89, v97, v[100:103]
	v_mfma_f32_16x16x4_f32 v[100:103], v90, v98, v[100:103]
	v_mfma_f32_16x16x4_f32 v[100:103], v91, v99, v[100:103]
	global_load_dwordx4 v[88:91], v59, s[10:11]
	s_cmp_lt_u32 s0, 0x1ff
	s_cselect_b32 s12, 0x400, 0
	s_add_u32 s10, s10, s12
	s_addc_u32 s11, s11, 0
	s_and_b32 s12, s0, 3
	s_cmp_eq_u32 s12, s100
	s_cbranch_scc0 .Lgd_upd
	ds_read_b128 v[72:75], v147 offset:1024
	ds_read_b128 v[76:79], v147 offset:4096
	ds_read_b128 v[80:83], v147 offset:7168
	ds_read_b128 v[84:87], v147 offset:10240
	s_waitcnt lgkmcnt(0)
	v_add_f32_e32 v72, v72, v76
	v_add_f32_e32 v80, v80, v84
	v_add_f32_e32 v73, v73, v77
	v_add_f32_e32 v81, v81, v85
	v_add_f32_e32 v74, v74, v78
	v_add_f32_e32 v82, v82, v86
	v_add_f32_e32 v75, v75, v79
	v_add_f32_e32 v83, v83, v87
	v_add_f32_e32 v104, v72, v80
	v_add_f32_e32 v105, v73, v81
	v_add_f32_e32 v106, v74, v82
	v_add_f32_e32 v107, v75, v83
	s_nop 7
	s_nop 1
	v_mfma_f32_16x16x4_f32 v[104:107], v92, v100, v[104:107]
	v_mfma_f32_16x16x4_f32 v[104:107], v93, v101, v[104:107]
	v_mfma_f32_16x16x4_f32 v[104:107], v94, v102, v[104:107]
	v_mfma_f32_16x16x4_f32 v[104:107], v95, v103, v[104:107]
.Lgd_upd:
	s_nop 2
	v_mfma_f32_16x16x4_f32 v[12:15], v36, v100, v[12:15]
	v_mfma_f32_16x16x4_f32 v[16:19], v40, v100, v[16:19]
	v_mfma_f32_16x16x4_f32 v[12:15], v37, v101, v[12:15]
	v_mfma_f32_16x16x4_f32 v[16:19], v41, v101, v[16:19]
	v_mfma_f32_16x16x4_f32 v[12:15], v38, v102, v[12:15]
	v_mfma_f32_16x16x4_f32 v[16:19], v42, v102, v[16:19]
	v_mfma_f32_16x16x4_f32 v[12:15], v39, v103, v[12:15]
	v_mfma_f32_16x16x4_f32 v[16:19], v43, v103, v[16:19]
	global_load_dwordx4 v[92:95], v59, s[14:15]
	s_cmp_lt_u32 s0, 0x1ff
	s_cselect_b32 s101, 0x400, 0
	s_add_u32 s14, s14, s101
	s_addc_u32 s15, s15, 0
	s_cmp_eq_u32 s12, s100
	s_cbranch_scc0 .Lgd_noout
	s_nop 7
	s_nop 3
	v_mul_f32_e32 v104, v104, v52
	v_mul_f32_e32 v105, v105, v53
	v_mul_f32_e32 v106, v106, v54
	v_mul_f32_e32 v107, v107, v55
	v_cvt_pk_bf16_f32 v104, v104, v104
	v_cvt_pk_bf16_f32 v105, v105, v105
	v_cvt_pk_bf16_f32 v106, v106, v106
	v_cvt_pk_bf16_f32 v107, v107, v107
.Lgd_noout:
	s_nop 6
	v_mul_f32_e32 v12, v12, v56
	v_mul_f32_e32 v13, v13, v56
	v_mul_f32_e32 v14, v14, v56
	v_mul_f32_e32 v15, v15, v56
	v_mul_f32_e32 v16, v16, v56
	v_mul_f32_e32 v17, v17, v56
	v_mul_f32_e32 v18, v18, v56
	v_mul_f32_e32 v19, v19, v56
	s_mov_b32 s1, s2
	s_add_i32 s0, s0, 1
	s_cmp_lg_u32 s0, 513
	s_cbranch_scc1 .Lgd_chunk
	s_waitcnt vmcnt(0) lgkmcnt(0)
	s_cmp_eq_u32 s100, 0
	s_cbranch_scc0 .Lgd_fin
	global_store_short v57, v104, s[8:9]
	global_store_short v57, v105, s[8:9] offset:2048
	global_store_short v58, v106, s[8:9]
	global_store_short v58, v107, s[8:9] offset:2048
.Lgd_fin:
	s_waitcnt vmcnt(0)
	s_setprio 0
